# v_rm_m1 + M1 tile order: a workgroup's four tiles share one row tile (row statistics loaded once, activation rows reused)
# speedup vs baseline: 1.0031x; 1.0031x over previous
.LBB0_255:
	s_or_b64 exec, exec, s[4:5]
	s_sub_i32 s4, s31, 32
	s_lshr_b32 s8, s4, 3
	s_lshl_b32 s4, s2, 2
	s_ashr_i32 s92, s2, 5
	s_bfe_u32 s9, s2, 0x20001
	s_and_b32 s10, s4, 4
	v_readlane_b32 s11, v253, 2
	s_cmp_gt_i32 s11, 31
	s_cselect_b64 s[4:5], -1, 0
	s_and_b64 s[4:5], s[4:5], exec
	s_cselect_b32 s93, s9, 0
	s_cselect_b32 s94, s8, s92
	s_lshl_b32 s8, s30, 2
	s_cmp_gt_i32 s11, 31
	s_cselect_b64 s[4:5], -1, 0
	s_and_b64 s[4:5], s[4:5], exec
	s_cselect_b32 s95, s10, s8
	s_sub_i32 s8, s11, 32
	s_cmp_gt_i32 s11, 31
	s_cselect_b64 s[4:5], -1, 0
	v_cndmask_b32_e64 v2, 0, 1, s[4:5]
	s_and_b64 s[4:5], s[4:5], exec
	v_readlane_b32 s4, v253, 0
	s_cselect_b32 s8, s8, 0x100000
	v_readlane_b32 s5, v253, 1
	s_add_u32 s4, s4, 0x1200
	s_addc_u32 s5, s5, 0
	v_writelane_b32 v253, s4, 4
	s_cmp_lt_i32 s92, 8
	s_mov_b32 s87, 0
	v_writelane_b32 v253, s5, 5
	s_cselect_b64 s[4:5], -1, 0
	s_lshr_b32 s9, s92, 30
	s_add_i32 s9, s92, s9
	s_ashr_i32 s10, s9, 2
	s_and_b32 s9, s9, -4
	s_lshl_b32 s12, s30, 1
	s_sub_i32 s78, s92, s9
	s_lshl_b32 s9, s3, 16
	s_add_i32 s74, s12, s10
	s_lshl_b32 s89, s3, 23
	v_writelane_b32 v253, s9, 6
	s_lshl_b32 s80, s3, 24
	s_lshl_b32 s9, s54, 8
	s_add_u32 s6, s6, s9
	s_addc_u32 s7, s7, 0
	s_add_u32 s14, s6, 0x1400
	s_addc_u32 s15, s7, 0
	s_add_u32 s82, s6, 0x2400
	s_addc_u32 s83, s7, 0
	s_add_u32 s96, s33, 0x4200
	s_addc_u32 s97, s53, 0
	s_add_u32 s6, s33, 0x7400
	s_addc_u32 s7, s53, 0
	v_writelane_b32 v253, s14, 7
	s_add_u32 s42, s33, 0x7500
	s_addc_u32 s43, s53, 0
	v_writelane_b32 v253, s15, 8
	s_lshl_b32 s81, s3, 25
	s_lshl_b32 s84, s3, 18
	v_writelane_b32 v253, s6, 9
	s_cmp_lt_i32 s92, 20
	s_mul_hi_i32 s3, s92, 0x66666667
	v_writelane_b32 v253, s7, 10
	s_cselect_b64 s[6:7], -1, 0
	v_writelane_b32 v253, s6, 11
	s_movk_i32 s88, 0x1000
	s_movk_i32 s33, 0x80
	v_writelane_b32 v253, s7, 12
	s_lshr_b32 s6, s3, 31
	s_ashr_i32 s3, s3, 2
	s_add_i32 s3, s3, s6
	s_add_i32 s14, s12, s3
	s_mov_b32 s6, s14
	s_ashr_i32 s15, s14, 31
	v_writelane_b32 v253, s6, 13
	s_mul_i32 s3, s3, 10
	s_sub_i32 s16, s92, s3
	v_writelane_b32 v253, s7, 14
	s_lshl_b64 s[6:7], s[14:15], 19
	v_writelane_b32 v253, s6, 15
	s_ashr_i32 s17, s16, 31
	v_and_b32_e32 v234, 63, v0
	v_writelane_b32 v253, s7, 16
	s_mov_b32 s6, s16
	v_writelane_b32 v253, s6, 17
	v_mov_b32_e32 v4, 0
	v_cndmask_b32_e64 v235, 0, 1, s[4:5]
	v_writelane_b32 v253, s7, 18
	s_lshl_b64 s[6:7], s[16:17], 19
	v_writelane_b32 v253, s6, 19
	s_cmp_lt_u32 s8, 32
	s_mov_b32 s16, s78
	v_writelane_b32 v253, s7, 20
	s_cselect_b64 s[6:7], -1, 0
	v_writelane_b32 v253, s6, 21
	s_lshr_b32 s86, s8, 3
	v_mov_b32_e32 v236, 0x358637bd
	v_writelane_b32 v253, s7, 22
	s_and_b32 s6, s8, 7
	s_lshl_b32 s3, s6, 19
	v_writelane_b32 v253, s3, 23
	s_lshl_b64 s[8:9], s[86:87], 22
	v_writelane_b32 v253, s8, 24
	v_mov_b32_e32 v237, 0x260
	v_mov_b32_e32 v238, 1
	v_writelane_b32 v253, s9, 25
	v_mov_b32_e32 v239, 0x3d2aaaab
	v_readlane_b32 s3, v253, 3
	s_cmpk_lt_i32 s3, 0x1000
	s_cselect_b64 s[8:9], -1, 0
	s_and_b32 s79, s52, 3
	v_writelane_b32 v253, s8, 26
	s_cmpk_lt_i32 s3, 0x800
	v_mov_b32_e32 v240, 0x1f0
	v_writelane_b32 v253, s9, 27
	s_cselect_b64 s[8:9], -1, 0
	v_writelane_b32 v253, s8, 28
	s_ashr_i32 s3, s2, 6
	v_mov_b32_e32 v241, 0x41b17218
	v_writelane_b32 v253, s9, 29
	v_writelane_b32 v253, s3, 30
	s_and_b32 s3, s11, 15
	s_cmpk_lt_i32 s11, 0x80
	v_writelane_b32 v253, s3, 31
	s_cselect_b64 s[8:9], -1, 0
	v_writelane_b32 v253, s8, 32
	s_ashr_i32 s2, s2, 3
	s_lshl_b32 s3, s11, 6
	v_writelane_b32 v253, s9, 33
	s_andn2_b32 s2, s2, 31
	v_writelane_b32 v253, s3, 34
	s_ashr_i32 s3, s2, 31
	s_lshl_b64 s[2:3], s[2:3], 9
	s_cmp_lt_i32 s92, 32
	s_cselect_b64 s[8:9], -1, 0
	s_lshr_b32 s7, s92, 28
	v_writelane_b32 v253, s8, 35
	s_add_i32 s7, s92, s7
	s_lshl_b32 s6, s6, 8
	v_writelane_b32 v253, s9, 36
	s_ashr_i32 s8, s7, 4
	s_and_b32 s7, s7, -16
	s_sub_i32 s14, s92, s7
	s_lshl_b32 s7, s86, 8
	v_writelane_b32 v253, s7, 37
	v_writelane_b32 v253, s6, 38
	v_readfirstlane_b32 s6, v2
	s_add_i32 s10, s12, s8
	s_lshl_b32 s8, s52, 6
	v_writelane_b32 v253, s6, 39
	s_lshr_b32 s6, s31, 3
	s_lshl_b32 s7, s6, 12
	s_add_i32 s7, s7, s8
	s_lshl_b32 s6, s6, 6
	v_writelane_b32 v253, s7, 40
	s_add_i32 s6, s52, s6
	s_lshl_b32 s7, s30, 3
	s_add_i32 s6, s6, s7
	s_add_i32 s7, s6, 0x600
	v_writelane_b32 v253, s7, 41
	s_lshl_b32 s7, s6, 8
	v_writelane_b32 v253, s7, 42
	s_lshl_b32 s7, s6, 11
	v_writelane_b32 v253, s7, 43
	s_lshl_b32 s7, s6, 3
	v_writelane_b32 v253, s7, 44
	s_lshl_b32 s6, s6, 1
	v_writelane_b32 v253, s6, 45
	s_lshl_b64 s[2:3], s[2:3], 2
	v_writelane_b32 v253, s2, 46
	s_ashr_i32 s11, s10, 31
	s_ashr_i32 s15, s14, 31
	v_writelane_b32 v253, s3, 47
	s_add_i32 s2, 0, 0x20168
	v_writelane_b32 v253, s2, 48
	s_add_i32 s2, 0, 0x2016c
	v_writelane_b32 v253, s2, 49
	s_lshr_b32 s10, s92, 2
	s_add_i32 s10, s10, s12
	s_mov_b32 s11, 0
	s_and_b32 s14, s92, 3
	s_lshl_b32 s14, s14, 2
	s_mov_b32 s15, 0
	s_mov_b32 s2, s10
	v_writelane_b32 v253, s2, 50
	s_ashr_i32 s75, s74, 31
	s_ashr_i32 s17, s78, 31
	v_writelane_b32 v253, s3, 51
	s_lshl_b64 s[2:3], s[10:11], 19
	v_writelane_b32 v253, s2, 52
	s_mov_b32 s86, s12
	s_lshl_b32 s41, s30, 9
	v_writelane_b32 v253, s3, 53
	s_mov_b32 s2, s14
	v_writelane_b32 v253, s2, 54
	s_mov_b32 s44, 0xf800000
	s_movk_i32 s70, 0xd0
	v_writelane_b32 v253, s3, 55
	s_lshl_b64 s[2:3], s[14:15], 19
	v_writelane_b32 v253, s2, 56
	s_movk_i32 s71, 0xe0
	s_movk_i32 s76, 0xf0
	v_writelane_b32 v253, s3, 57
	s_lshl_b64 s[2:3], s[74:75], 19
	v_writelane_b32 v253, s2, 58
	s_movk_i32 s77, 0x1400
	s_mov_b32 s72, 0x40000
	v_writelane_b32 v253, s3, 59
	s_lshl_b64 s[2:3], s[16:17], 19
	v_writelane_b32 v253, s2, 60
	s_mov_b32 s46, 0
	s_mov_b64 s[68:69], 0x80
	v_writelane_b32 v253, s3, 61
	s_lshl_b64 s[2:3], s[16:17], 17
	v_writelane_b32 v253, s2, 62
	s_nop 1
	v_writelane_b32 v253, s3, 63
	s_lshl_b64 s[2:3], s[74:75], 21
	v_writelane_b32 v254, s2, 0
	s_nop 1
	v_writelane_b32 v254, s3, 1
	v_writelane_b32 v254, s16, 2
	s_lshl_b64 s[2:3], s[16:17], 21
	s_nop 0
	v_writelane_b32 v254, s17, 3
	v_writelane_b32 v254, s2, 4
	s_nop 1
	v_writelane_b32 v254, s3, 5
	v_writelane_b32 v254, s90, 6
	s_nop 1
	v_writelane_b32 v254, s91, 7
	v_writelane_b32 v254, s85, 8
	v_writelane_b32 v254, s92, 9
	v_writelane_b32 v254, s93, 10
	v_writelane_b32 v254, s94, 11
	v_writelane_b32 v254, s95, 12
	v_writelane_b32 v254, s86, 13
	v_writelane_b32 v254, s89, 14
	v_writelane_b32 v254, s80, 15
	v_writelane_b32 v254, s82, 16
	s_nop 1
	v_writelane_b32 v254, s83, 17
	v_writelane_b32 v254, s96, 18
	s_nop 1
	v_writelane_b32 v254, s97, 19
	v_writelane_b32 v254, s42, 20
	s_nop 1
	v_writelane_b32 v254, s43, 21
	v_writelane_b32 v254, s81, 22
	v_writelane_b32 v254, s84, 23
	v_writelane_b32 v254, s79, 24
	v_writelane_b32 v254, s41, 25
	s_branch .LBB0_259

.LBB0_937:
	s_add_i32 s57, s57, 1
	s_lshl_b32 s13, s92, 2
	s_add_i32 s13, s13, s57
	s_cmp_lt_i32 s57, 4
	s_cselect_b64 s[20:21], -1, 0
	s_cmp_gt_i32 s57, 3
	s_cbranch_scc1 .LBB0_939
	s_ashr_i32 s12, s13, 31
	s_lshr_b32 s12, s12, 28
	s_add_i32 s14, s13, s12
	s_ashr_i32 s12, s14, 4
	s_and_b32 s14, s14, -16
	s_add_i32 s12, s12, s86
	s_sub_i32 s14, s13, s14
